# v61 + helper's decay-row load (kept only as a cache prefetch for the scan waves) shrunk from 16 to 4 bytes per lane
# speedup vs baseline: 1.0054x; 1.0006x over previous
.LBB0_730:
	v_ashrrev_i32_e32 v107, 31, v106
	v_lshlrev_b64 v[98:99], 11, v[106:107]
	v_lshl_add_u64 v[98:99], v[98:99], 0, v[120:121]
	v_lshlrev_b64 v[100:101], 1, v[98:99]
	v_lshl_add_u64 v[102:103], s[12:13], 0, v[100:101]
	v_lshl_add_u64 v[104:105], s[18:19], 0, v[100:101]
	v_lshl_add_u64 v[100:101], s[94:95], 0, v[100:101]
	v_lshlrev_b64 v[98:99], 2, v[98:99]
	v_lshlrev_b64 v[106:107], 12, v[106:107]
	global_load_dwordx2 v[160:161], v[102:103], off
	global_load_dwordx2 v[162:163], v[104:105], off
	global_load_dwordx2 v[158:159], v[100:101], off
	v_lshl_add_u64 v[100:101], s[28:29], 0, v[98:99]
	v_lshl_add_u64 v[98:99], s[30:31], 0, v[98:99]
	v_lshl_add_u64 v[106:107], v[130:131], 0, v[106:107]
	global_load_dword v102, v[100:101], off
	global_load_dwordx2 v[156:157], v[106:107], off
	s_waitcnt vmcnt(18)
	v_pk_add_f32 v[110:111], v[12:13], -1.0 op_sel_hi:[1,0]
	global_load_dwordx4 v[98:101], v[98:99], off
	v_pk_add_f32 v[112:113], v[10:11], -1.0 op_sel_hi:[1,0]
	v_lshlrev_b32_e32 v188, 16, v142
	v_and_b32_e32 v189, 0xffff0000, v142
	v_lshlrev_b32_e32 v190, 16, v143
	v_and_b32_e32 v191, 0xffff0000, v143
	v_lshlrev_b32_e32 v106, 16, v140
	v_and_b32_e32 v107, 0xffff0000, v140
	v_lshlrev_b32_e32 v108, 16, v141
	v_and_b32_e32 v109, 0xffff0000, v141
	v_pk_fma_f32 v[110:111], v[8:9], v[110:111], 1.0 op_sel_hi:[1,1,0]
	v_pk_fma_f32 v[112:113], v[6:7], v[112:113], 1.0 op_sel_hi:[1,1,0]
	v_pk_mul_f32 v[108:109], v[110:111], v[108:109]
	v_pk_mul_f32 v[106:107], v[112:113], v[106:107]
	v_lshlrev_b32_e32 v110, 16, v134
	v_and_b32_e32 v111, 0xffff0000, v134
	v_lshlrev_b32_e32 v112, 16, v135
	v_and_b32_e32 v113, 0xffff0000, v135
	v_xor_b32_e32 v143, 0x80000000, v191
	v_xor_b32_e32 v142, 0x80000000, v190
	v_xor_b32_e32 v141, 0x80000000, v189
	v_xor_b32_e32 v140, 0x80000000, v188
	v_pk_mul_f32 v[12:13], v[12:13], v[190:191]
	v_pk_mul_f32 v[10:11], v[10:11], v[188:189]
	ds_write_b128 v124, v[140:143] offset:20480
	ds_write_b128 v124, v[10:13] offset:20992
	ds_write_b128 v124, v[106:109] offset:21248
	ds_write_b128 v124, v[110:113] offset:21504
	s_and_saveexec_b64 s[40:41], s[6:7]
	s_cbranch_execz .LBB0_732
	s_waitcnt vmcnt(18)
	v_lshlrev_b32_e32 v10, 16, v136
	v_and_b32_e32 v11, 0xffff0000, v136
	v_lshlrev_b32_e32 v12, 16, v137
	v_and_b32_e32 v13, 0xffff0000, v137
	ds_write_b128 v186, v[10:13] offset:43008

.LBB0_756:
	v_ashrrev_i32_e32 v107, 31, v106
	v_lshlrev_b64 v[10:11], 11, v[106:107]
	v_lshl_add_u64 v[10:11], v[10:11], 0, v[120:121]
	v_lshlrev_b64 v[12:13], 1, v[10:11]
	v_lshl_add_u64 v[14:15], s[12:13], 0, v[12:13]
	v_lshl_add_u64 v[16:17], s[18:19], 0, v[12:13]
	v_lshl_add_u64 v[12:13], s[94:95], 0, v[12:13]
	v_lshlrev_b64 v[10:11], 2, v[10:11]
	v_lshlrev_b64 v[106:107], 12, v[106:107]
	global_load_dwordx2 v[140:141], v[14:15], off
	global_load_dwordx2 v[142:143], v[16:17], off
	global_load_dwordx2 v[134:135], v[12:13], off
	v_lshl_add_u64 v[12:13], s[28:29], 0, v[10:11]
	v_lshl_add_u64 v[10:11], s[30:31], 0, v[10:11]
	v_lshl_add_u64 v[106:107], v[130:131], 0, v[106:107]
	global_load_dword v14, v[12:13], off
	global_load_dwordx2 v[136:137], v[106:107], off
	s_waitcnt vmcnt(19)
	v_pk_add_f32 v[110:111], v[20:21], -1.0 op_sel_hi:[1,0]
	global_load_dwordx4 v[10:13], v[10:11], off
	v_pk_add_f32 v[112:113], v[18:19], -1.0 op_sel_hi:[1,0]
	v_lshlrev_b32_e32 v188, 16, v146
	v_and_b32_e32 v189, 0xffff0000, v146
	v_lshlrev_b32_e32 v190, 16, v147
	v_and_b32_e32 v191, 0xffff0000, v147
	v_lshlrev_b32_e32 v106, 16, v144
	v_and_b32_e32 v107, 0xffff0000, v144
	v_lshlrev_b32_e32 v108, 16, v145
	v_and_b32_e32 v109, 0xffff0000, v145
	v_pk_fma_f32 v[110:111], v[8:9], v[110:111], 1.0 op_sel_hi:[1,1,0]
	v_pk_fma_f32 v[112:113], v[6:7], v[112:113], 1.0 op_sel_hi:[1,1,0]
	v_pk_mul_f32 v[108:109], v[110:111], v[108:109]
	v_pk_mul_f32 v[106:107], v[112:113], v[106:107]
	v_lshlrev_b32_e32 v110, 16, v138
	v_and_b32_e32 v111, 0xffff0000, v138
	v_lshlrev_b32_e32 v112, 16, v139
	v_and_b32_e32 v113, 0xffff0000, v139
	v_xor_b32_e32 v147, 0x80000000, v191
	v_xor_b32_e32 v146, 0x80000000, v190
	v_xor_b32_e32 v145, 0x80000000, v189
	v_xor_b32_e32 v144, 0x80000000, v188
	v_pk_mul_f32 v[20:21], v[20:21], v[190:191]
	v_pk_mul_f32 v[18:19], v[18:19], v[188:189]
	ds_write_b128 v124, v[144:147]
	ds_write_b128 v124, v[18:21] offset:512
	ds_write_b128 v124, v[106:109] offset:768
	ds_write_b128 v124, v[110:113] offset:1024
	s_and_saveexec_b64 s[40:41], s[6:7]
	v_lshlrev_b32_e32 v18, 16, v132
	v_and_b32_e32 v19, 0xffff0000, v132
	v_lshlrev_b32_e32 v20, 16, v133
	v_and_b32_e32 v21, 0xffff0000, v133
	ds_write_b128 v186, v[18:21] offset:40960
	s_or_b64 exec, exec, s[40:41]
	v_pk_mul_f32 v[18:19], v[108:109], v[112:113]
	v_pk_mul_f32 v[20:21], v[106:107], v[110:111]
	v_mul_f32_e32 v19, v5, v19
	v_mul_f32_e32 v21, v3, v21
	v_fmac_f32_e32 v21, v2, v20
	v_fmac_f32_e32 v19, v4, v18
	v_add_f32_e32 v18, v21, v19
	v_mov_b32_e32 v20, 0
	s_nop 0
	v_add_f32_dpp v18, v18, v18 row_ror:8 row_mask:0xf bank_mask:0xf bound_ctrl:1
	s_nop 1
	v_add_f32_dpp v18, v18, v18 row_ror:4 row_mask:0xf bank_mask:0xf bound_ctrl:1
	s_nop 1
	v_add_f32_dpp v19, v18, v18 row_ror:2 row_mask:0xf bank_mask:0xf bound_ctrl:1
	s_nop 1
	v_mov_b32_dpp v20, v19 row_ror:1 row_mask:0xf bank_mask:0xf
	s_and_saveexec_b64 s[40:41], s[8:9]
	s_cbranch_execz .LBB0_764
	s_and_b64 vcc, exec, s[4:5]
	s_mov_b64 s[52:53], -1
	s_cbranch_vccnz .LBB0_761
	v_lshl_add_u32 v18, s46, 4, v167
	v_sub_u32_e32 v18, 0x1fdf, v18
	s_mov_b64 s[52:53], 0

.LBB0_782:
	v_ashrrev_i32_e32 v107, 31, v106
	v_lshlrev_b64 v[18:19], 11, v[106:107]
	v_lshl_add_u64 v[18:19], v[18:19], 0, v[120:121]
	v_lshlrev_b64 v[20:21], 1, v[18:19]
	v_lshl_add_u64 v[22:23], s[12:13], 0, v[20:21]
	v_lshl_add_u64 v[24:25], s[18:19], 0, v[20:21]
	v_lshl_add_u64 v[20:21], s[94:95], 0, v[20:21]
	v_lshlrev_b64 v[18:19], 2, v[18:19]
	v_lshlrev_b64 v[106:107], 12, v[106:107]
	global_load_dwordx2 v[144:145], v[22:23], off
	global_load_dwordx2 v[146:147], v[24:25], off
	global_load_dwordx2 v[138:139], v[20:21], off
	v_lshl_add_u64 v[20:21], s[28:29], 0, v[18:19]
	v_lshl_add_u64 v[18:19], s[30:31], 0, v[18:19]
	v_lshl_add_u64 v[106:107], v[130:131], 0, v[106:107]
	global_load_dword v22, v[20:21], off
	global_load_dwordx2 v[132:133], v[106:107], off
	s_waitcnt vmcnt(22)
	v_pk_add_f32 v[110:111], v[92:93], -1.0 op_sel_hi:[1,0]
	global_load_dwordx4 v[18:21], v[18:19], off
	v_pk_add_f32 v[112:113], v[90:91], -1.0 op_sel_hi:[1,0]
	v_lshlrev_b32_e32 v190, 16, v154
	v_and_b32_e32 v191, 0xffff0000, v154
	v_lshlrev_b32_e32 v154, 16, v155
	v_and_b32_e32 v155, 0xffff0000, v155
	v_lshlrev_b32_e32 v106, 16, v152
	v_and_b32_e32 v107, 0xffff0000, v152
	v_lshlrev_b32_e32 v108, 16, v153
	v_and_b32_e32 v109, 0xffff0000, v153
	v_pk_fma_f32 v[110:111], v[8:9], v[110:111], 1.0 op_sel_hi:[1,1,0]
	v_pk_fma_f32 v[112:113], v[6:7], v[112:113], 1.0 op_sel_hi:[1,1,0]
	v_pk_mul_f32 v[108:109], v[110:111], v[108:109]
	v_pk_mul_f32 v[106:107], v[112:113], v[106:107]
	v_lshlrev_b32_e32 v110, 16, v150
	v_and_b32_e32 v111, 0xffff0000, v150
	v_lshlrev_b32_e32 v112, 16, v151
	v_and_b32_e32 v113, 0xffff0000, v151
	v_xor_b32_e32 v153, 0x80000000, v155
	v_xor_b32_e32 v152, 0x80000000, v154
	v_xor_b32_e32 v151, 0x80000000, v191
	v_xor_b32_e32 v150, 0x80000000, v190
	v_pk_mul_f32 v[92:93], v[92:93], v[154:155]
	v_pk_mul_f32 v[90:91], v[90:91], v[190:191]
	ds_write_b128 v124, v[150:153] offset:20480
	ds_write_b128 v124, v[90:93] offset:20992
	ds_write_b128 v124, v[106:109] offset:21248
	ds_write_b128 v124, v[110:113] offset:21504
	s_and_saveexec_b64 s[52:53], s[6:7]
	s_cbranch_execz .LBB0_784
	s_waitcnt vmcnt(22)
	v_lshlrev_b32_e32 v90, 16, v148
	v_and_b32_e32 v91, 0xffff0000, v148
	v_lshlrev_b32_e32 v92, 16, v149
	v_and_b32_e32 v93, 0xffff0000, v149
	ds_write_b128 v186, v[90:93] offset:43008

.LBB0_809:
	v_ashrrev_i32_e32 v107, 31, v106
	v_lshlrev_b64 v[90:91], 11, v[106:107]
	v_lshl_add_u64 v[90:91], v[90:91], 0, v[120:121]
	v_lshlrev_b64 v[92:93], 1, v[90:91]
	v_lshl_add_u64 v[94:95], s[12:13], 0, v[92:93]
	v_lshl_add_u64 v[96:97], s[18:19], 0, v[92:93]
	v_lshl_add_u64 v[92:93], s[94:95], 0, v[92:93]
	v_lshlrev_b64 v[90:91], 2, v[90:91]
	v_lshlrev_b64 v[106:107], 12, v[106:107]
	global_load_dwordx2 v[152:153], v[94:95], off
	global_load_dwordx2 v[154:155], v[96:97], off
	global_load_dwordx2 v[150:151], v[92:93], off
	v_lshl_add_u64 v[92:93], s[28:29], 0, v[90:91]
	v_lshl_add_u64 v[90:91], s[30:31], 0, v[90:91]
	v_lshl_add_u64 v[106:107], v[130:131], 0, v[106:107]
	global_load_dword v94, v[92:93], off
	global_load_dwordx2 v[148:149], v[106:107], off
	s_waitcnt vmcnt(23)
	v_pk_add_f32 v[110:111], v[100:101], -1.0 op_sel_hi:[1,0]
	global_load_dwordx4 v[90:93], v[90:91], off
	v_pk_add_f32 v[112:113], v[98:99], -1.0 op_sel_hi:[1,0]
	v_lshlrev_b32_e32 v190, 16, v162
	v_and_b32_e32 v191, 0xffff0000, v162
	v_lshlrev_b32_e32 v162, 16, v163
	v_and_b32_e32 v163, 0xffff0000, v163
	v_lshlrev_b32_e32 v106, 16, v160
	v_and_b32_e32 v107, 0xffff0000, v160
	v_lshlrev_b32_e32 v108, 16, v161
	v_and_b32_e32 v109, 0xffff0000, v161
	v_pk_fma_f32 v[110:111], v[8:9], v[110:111], 1.0 op_sel_hi:[1,1,0]
	v_pk_fma_f32 v[112:113], v[6:7], v[112:113], 1.0 op_sel_hi:[1,1,0]
	v_pk_mul_f32 v[108:109], v[110:111], v[108:109]
	v_pk_mul_f32 v[106:107], v[112:113], v[106:107]
	v_lshlrev_b32_e32 v110, 16, v158
	v_and_b32_e32 v111, 0xffff0000, v158
	v_lshlrev_b32_e32 v112, 16, v159
	v_and_b32_e32 v113, 0xffff0000, v159
	v_xor_b32_e32 v161, 0x80000000, v163
	v_xor_b32_e32 v160, 0x80000000, v162
	v_xor_b32_e32 v159, 0x80000000, v191
	v_xor_b32_e32 v158, 0x80000000, v190
	v_pk_mul_f32 v[100:101], v[100:101], v[162:163]
	v_pk_mul_f32 v[98:99], v[98:99], v[190:191]
	ds_write_b128 v124, v[158:161]
	ds_write_b128 v124, v[98:101] offset:512
	ds_write_b128 v124, v[106:109] offset:768
	ds_write_b128 v124, v[110:113] offset:1024
	s_and_saveexec_b64 s[42:43], s[6:7]
	v_lshlrev_b32_e32 v98, 16, v156
	v_and_b32_e32 v99, 0xffff0000, v156
	v_lshlrev_b32_e32 v100, 16, v157
	v_and_b32_e32 v101, 0xffff0000, v157
	ds_write_b128 v186, v[98:101] offset:40960
	s_or_b64 exec, exec, s[42:43]
	v_pk_mul_f32 v[98:99], v[108:109], v[112:113]
	v_pk_mul_f32 v[100:101], v[106:107], v[110:111]
	v_mul_f32_e32 v99, v5, v99
	v_mul_f32_e32 v101, v3, v101
	v_fmac_f32_e32 v101, v2, v100
	v_fmac_f32_e32 v99, v4, v98
	v_add_f32_e32 v98, v101, v99
	v_mov_b32_e32 v100, 0
	s_nop 0
	v_add_f32_dpp v98, v98, v98 row_ror:8 row_mask:0xf bank_mask:0xf bound_ctrl:1
	s_nop 1
	v_add_f32_dpp v98, v98, v98 row_ror:4 row_mask:0xf bank_mask:0xf bound_ctrl:1
	s_nop 1
	v_add_f32_dpp v99, v98, v98 row_ror:2 row_mask:0xf bank_mask:0xf bound_ctrl:1
	s_nop 1
	v_mov_b32_dpp v100, v99 row_ror:1 row_mask:0xf bank_mask:0xf
	s_and_saveexec_b64 s[42:43], s[8:9]
	s_cbranch_execz .LBB0_817
	s_and_b64 vcc, exec, s[4:5]
	s_mov_b64 s[52:53], -1
	s_cbranch_vccnz .LBB0_814
	v_lshl_add_u32 v98, s47, 4, v167
	v_sub_u32_e32 v98, 0x1fbf, v98
	s_mov_b64 s[52:53], 0
